# epi9: P9 epilogue - second column-half gain/scale/shift loads hoisted ahead of the first half's 16 output stores (no mid-stream store drain)
# speedup vs baseline: 1.0004x; 1.0002x over previous
.LBB0_749:
	s_or_b64 exec, exec, s[6:7]
	v_lshlrev_b32_e32 v2, 2, v225
	s_waitcnt lgkmcnt(0)
	v_ashrrev_i32_e32 v3, 31, v2
	v_lshl_add_u64 v[2:3], v[2:3], 2, s[30:31]
	s_barrier
	v_lshl_add_u64 v[4:5], v[2:3], 0, v[196:197]
	global_load_dwordx4 v[8:11], v[4:5], off
	v_lshl_add_u64 v[4:5], v[2:3], 0, v[176:177]
	global_load_dwordx4 v[12:15], v[4:5], off
	v_lshl_add_u64 v[4:5], v[2:3], 0, v[168:169]
	global_load_dwordx4 v[154:157], v[4:5], off
	v_lshl_add_u64 v[4:5], v[2:3], 0, v[160:161]
	global_load_dwordx4 v[158:161], v[4:5], off
	v_lshl_add_u64 v[4:5], v[2:3], 0, v[152:153]
	global_load_dwordx4 v[162:165], v[4:5], off
	v_lshl_add_u64 v[4:5], v[2:3], 0, v[148:149]
	global_load_dwordx4 v[166:169], v[4:5], off
	v_lshl_add_u64 v[6:7], v[2:3], 0, v[150:151]
	v_lshl_add_u64 v[0:1], v[2:3], 0, v[0:1]
	global_load_dwordx4 v[170:173], v[6:7], off
	global_load_dwordx4 v[174:177], v[0:1], off
	s_add_i32 s64, s64, s83
	v_add_u32_e32 v4, s64, v223
	s_add_u32 s64, s71, s66
	v_ashrrev_i32_e32 v5, 31, v4
	v_readlane_b32 s48, v254, 0
	s_addc_u32 s65, s72, s67
	v_lshlrev_b64 v[2:3], 2, v[4:5]
	v_readlane_b32 s52, v254, 4
	v_readlane_b32 s53, v254, 5
	s_add_u32 s66, s73, s66
	v_add_u32_e32 v132, 0x80, v4
	v_lshl_add_u64 v[0:1], s[52:53], 0, v[2:3]
	v_lshl_add_u64 v[4:5], s[64:65], 0, v[2:3]
	s_addc_u32 s67, s74, s67
	global_load_dwordx4 v[178:181], v[0:1], off offset:16
	global_load_dwordx4 v[192:195], v[0:1], off
	global_load_dwordx4 v[196:199], v[4:5], off offset:16
	global_load_dwordx4 v[200:203], v[4:5], off
	v_lshl_add_u64 v[4:5], s[66:67], 0, v[2:3]
	global_load_dwordx4 v[0:3], v[4:5], off offset:16
	s_nop 0
	global_load_dwordx4 v[4:7], v[4:5], off
	v_mov_b32_e32 v242, v132
	v_ashrrev_i32_e32 v243, 31, v132
	v_lshlrev_b64 v[242:243], 2, v[242:243]
	v_lshl_add_u64 v[244:245], s[64:65], 0, v[242:243]
	v_lshl_add_u64 v[246:247], s[52:53], 0, v[242:243]
	v_lshl_add_u64 v[248:249], s[66:67], 0, v[242:243]
	global_load_dwordx4 v[204:207], v[244:245], off
	global_load_dwordx4 v[208:211], v[246:247], off
	global_load_dwordx4 v[212:215], v[244:245], off offset:16
	global_load_dwordx4 v[226:229], v[246:247], off offset:16
	global_load_dwordx4 v[230:233], v[248:249], off
	global_load_dwordx4 v[234:237], v[248:249], off offset:16
	v_mov_b64_e32 v[182:183], s[58:59]
	v_readlane_b32 s54, v254, 6
	v_readlane_b32 s55, v254, 7
	v_ashrrev_i32_e32 v133, 31, v132
	v_readlane_b32 s49, v254, 1
	v_readlane_b32 s50, v254, 2
	v_readlane_b32 s51, v254, 3
	s_waitcnt vmcnt(19)
	v_mov_b32_e32 v134, v9
	v_mov_b32_e32 v135, v10
	v_mov_b32_e32 v9, v11
	s_waitcnt vmcnt(18)
	v_mov_b32_e32 v10, v13
	v_mov_b32_e32 v11, v14
	v_mov_b32_e32 v13, v15
	s_waitcnt vmcnt(17)
	v_mov_b32_e32 v14, v155
	v_mov_b32_e32 v15, v156
	v_mov_b32_e32 v155, v157
	s_waitcnt vmcnt(16)
	v_mov_b32_e32 v148, v159
	v_mov_b32_e32 v149, v160
	v_mov_b32_e32 v159, v161
	s_waitcnt vmcnt(15)
	v_mov_b32_e32 v150, v163
	v_mov_b32_e32 v151, v164
	v_mov_b32_e32 v163, v165
	v_pk_add_f32 v[8:9], v[134:135], v[8:9]
	v_pk_add_f32 v[10:11], v[10:11], v[12:13]
	v_pk_add_f32 v[12:13], v[14:15], v[154:155]
	v_pk_add_f32 v[14:15], v[148:149], v[158:159]
	v_pk_add_f32 v[134:135], v[150:151], v[162:163]
	v_mov_b32_e32 v150, v10
	v_mov_b32_e32 v151, v8
	v_mov_b32_e32 v8, v11
	v_mov_b32_e32 v10, v14
	v_mov_b32_e32 v11, v12
	v_mov_b32_e32 v12, v15
	v_pk_add_f32 v[8:9], v[150:151], v[8:9]
	v_pk_add_f32 v[10:11], v[10:11], v[12:13]
	ds_bpermute_b32 v13, v222, v9
	ds_bpermute_b32 v12, v222, v8
	ds_bpermute_b32 v15, v222, v11
	ds_bpermute_b32 v14, v222, v10
	s_waitcnt vmcnt(14)
	v_mov_b32_e32 v152, v167
	v_mov_b32_e32 v153, v168
	s_waitcnt lgkmcnt(2)
	v_pk_add_f32 v[8:9], v[8:9], v[12:13]
	ds_bpermute_b32 v13, v224, v9
	ds_bpermute_b32 v12, v224, v8
	s_waitcnt lgkmcnt(2)
	v_pk_add_f32 v[10:11], v[10:11], v[14:15]
	ds_bpermute_b32 v15, v224, v11
	ds_bpermute_b32 v14, v224, v10
	v_mov_b32_e32 v167, v169
	s_waitcnt lgkmcnt(2)
	v_pk_add_f32 v[8:9], v[8:9], v[12:13]
	v_pk_add_f32 v[148:149], v[152:153], v[166:167]
	v_pk_fma_f32 v[8:9], v[8:9], s[56:57], v[182:183] op_sel_hi:[1,0,0]
	v_mov_b32_e32 v150, v148
	v_mul_f32_e32 v12, 0x4b800000, v9
	v_cmp_gt_f32_e32 vcc, s91, v9
	v_mov_b32_e32 v151, v134
	v_mov_b32_e32 v134, v149
	v_cndmask_b32_e32 v9, v9, v12, vcc
	s_waitcnt lgkmcnt(0)
	v_pk_add_f32 v[10:11], v[10:11], v[14:15]
	v_rsq_f32_e32 v9, v9
	v_pk_add_f32 v[134:135], v[150:151], v[134:135]
	v_pk_fma_f32 v[10:11], v[10:11], s[56:57], v[182:183] op_sel_hi:[1,0,0]
	v_mul_f32_e32 v13, 0x4b800000, v8
	v_cmp_gt_f32_e64 s[0:1], s91, v8
	ds_bpermute_b32 v149, v222, v135
	ds_bpermute_b32 v148, v222, v134
	v_mul_f32_e32 v14, 0x4b800000, v11
	v_cndmask_b32_e64 v8, v8, v13, s[0:1]
	v_cmp_gt_f32_e64 s[6:7], s91, v11
	v_rsq_f32_e32 v12, v8
	s_waitcnt vmcnt(9)
	v_pk_add_f32 v[158:159], v[198:199], 1.0 op_sel_hi:[1,0]
	v_cndmask_b32_e64 v8, v11, v14, s[6:7]
	v_rsq_f32_e32 v13, v8
	v_mul_f32_e32 v8, 0x45800000, v9
	v_cndmask_b32_e32 v152, v9, v8, vcc
	v_mul_f32_e32 v8, 0x4b800000, v10
	v_cmp_gt_f32_e32 vcc, s91, v10
	v_mul_f32_e32 v14, 0x45800000, v12
	v_cndmask_b32_e64 v150, v12, v14, s[0:1]
	v_cndmask_b32_e32 v8, v10, v8, vcc
	v_rsq_f32_e32 v151, v8
	s_waitcnt lgkmcnt(0)
	v_pk_add_f32 v[8:9], v[134:135], v[148:149]
	ds_bpermute_b32 v11, v224, v9
	ds_bpermute_b32 v10, v224, v8
	v_mul_f32_e32 v12, 0x45800000, v13
	v_cndmask_b32_e64 v134, v13, v12, s[6:7]
	v_mov_b32_e32 v12, v175
	v_mov_b32_e32 v13, v176
	s_waitcnt lgkmcnt(0)
	v_pk_add_f32 v[8:9], v[8:9], v[10:11]
	v_mov_b32_e32 v11, v172
	v_pk_fma_f32 v[8:9], v[8:9], s[56:57], v[182:183] op_sel_hi:[1,0,0]
	v_mov_b32_e32 v175, v177
	v_mul_f32_e32 v10, 0x4b800000, v9
	v_cmp_gt_f32_e64 s[0:1], s91, v9
	v_pk_add_f32 v[12:13], v[12:13], v[174:175]
	v_cmp_gt_f32_e64 s[6:7], s91, v8
	v_cndmask_b32_e64 v9, v9, v10, s[0:1]
	v_mov_b32_e32 v10, v171
	v_mov_b32_e32 v171, v173
	v_pk_add_f32 v[10:11], v[10:11], v[170:171]
	v_mov_b32_e32 v14, v12
	v_mov_b32_e32 v15, v10
	v_mov_b32_e32 v10, v13
	v_pk_add_f32 v[10:11], v[14:15], v[10:11]
	ds_bpermute_b32 v13, v222, v11
	ds_bpermute_b32 v12, v222, v10
	v_rsq_f32_e32 v149, v9
	v_mul_f32_e32 v9, 0x4b800000, v8
	v_cndmask_b32_e64 v8, v8, v9, s[6:7]
	v_rsq_f32_e32 v15, v8
	s_waitcnt lgkmcnt(0)
	v_pk_add_f32 v[8:9], v[10:11], v[12:13]
	ds_bpermute_b32 v11, v224, v9
	ds_bpermute_b32 v10, v224, v8
	v_mul_f32_e32 v135, 0x45800000, v151
	v_cndmask_b32_e32 v148, v151, v135, vcc
	v_mul_f32_e32 v12, 0x45800000, v149
	v_pk_add_f32 v[160:161], v[196:197], 1.0 op_sel_hi:[1,0]
	s_waitcnt lgkmcnt(0)
	v_pk_add_f32 v[8:9], v[8:9], v[10:11]
	v_cndmask_b32_e64 v14, v149, v12, s[0:1]
	v_pk_fma_f32 v[8:9], v[8:9], s[56:57], v[182:183] op_sel_hi:[1,0,0]
	s_waitcnt vmcnt(8)
	v_pk_add_f32 v[156:157], v[200:201], 1.0 op_sel_hi:[1,0]
	v_mul_f32_e32 v10, 0x4b800000, v9
	v_cmp_gt_f32_e32 vcc, s91, v9
	v_cmp_gt_f32_e64 s[0:1], s91, v8
	v_pk_mul_f32 v[158:159], v[180:181], v[158:159]
	v_cndmask_b32_e32 v9, v9, v10, vcc
	v_rsq_f32_e32 v9, v9
	v_mul_f32_e32 v10, 0x4b800000, v8
	v_pk_mul_f32 v[160:161], v[178:179], v[160:161]
	v_pk_mul_f32 v[120:121], v[120:121], v[152:153] op_sel_hi:[1,0]
	v_pk_mul_f32 v[122:123], v[122:123], v[152:153] op_sel_hi:[1,0]
	v_cndmask_b32_e64 v8, v8, v10, s[0:1]
	v_mul_f32_e32 v10, 0x45800000, v9
	v_pk_mul_f32 v[156:157], v[192:193], v[156:157]
	v_lshl_add_u64 v[162:163], s[54:55], 0, v[240:241]
	s_waitcnt vmcnt(7)
	v_pk_fma_f32 v[122:123], v[122:123], v[158:159], v[2:3]
	v_pk_fma_f32 v[120:121], v[120:121], v[160:161], v[0:1]
	v_pk_mul_f32 v[108:109], v[108:109], v[150:151] op_sel_hi:[1,0]
	v_cndmask_b32_e32 v10, v9, v10, vcc
	global_store_dwordx4 v240, v[120:123], s[54:55] offset:16
	v_pk_mul_f32 v[104:105], v[104:105], v[150:151] op_sel_hi:[1,0]
	v_pk_mul_f32 v[106:107], v[106:107], v[150:151] op_sel_hi:[1,0]
	s_waitcnt vmcnt(1)
	v_pk_fma_f32 v[120:121], v[108:109], v[156:157], v[4:5]
	v_add_co_u32_e32 v108, vcc, s68, v162
	v_pk_fma_f32 v[106:107], v[106:107], v[158:159], v[2:3]
	s_nop 0
	v_addc_co_u32_e32 v109, vcc, 0, v163, vcc
	v_pk_fma_f32 v[104:105], v[104:105], v[160:161], v[0:1]
	v_pk_mul_f32 v[92:93], v[92:93], v[134:135] op_sel_hi:[1,0]
	global_store_dwordx4 v[108:109], v[104:107], off offset:16
	v_pk_mul_f32 v[88:89], v[88:89], v[134:135] op_sel_hi:[1,0]
	v_pk_mul_f32 v[90:91], v[90:91], v[134:135] op_sel_hi:[1,0]
	v_pk_fma_f32 v[104:105], v[92:93], v[156:157], v[4:5]
	v_add_co_u32_e32 v92, vcc, s95, v162
	v_pk_fma_f32 v[90:91], v[90:91], v[158:159], v[2:3]
	s_nop 0
	v_addc_co_u32_e32 v93, vcc, 0, v163, vcc
	v_pk_fma_f32 v[88:89], v[88:89], v[160:161], v[0:1]
	v_pk_mul_f32 v[76:77], v[76:77], v[148:149] op_sel_hi:[1,0]
	global_store_dwordx4 v[92:93], v[88:91], off offset:16
	v_pk_mul_f32 v[72:73], v[72:73], v[148:149] op_sel_hi:[1,0]
	v_pk_mul_f32 v[74:75], v[74:75], v[148:149] op_sel_hi:[1,0]
	v_pk_fma_f32 v[88:89], v[76:77], v[156:157], v[4:5]
	v_add_co_u32_e32 v76, vcc, s59, v162
	v_pk_fma_f32 v[74:75], v[74:75], v[158:159], v[2:3]
	s_nop 0
	v_addc_co_u32_e32 v77, vcc, 0, v163, vcc
	v_pk_fma_f32 v[72:73], v[72:73], v[160:161], v[0:1]
	v_mul_f32_e32 v12, 0x45800000, v15
	global_store_dwordx4 v[76:77], v[72:75], off offset:16
	v_cndmask_b32_e64 v12, v15, v12, s[6:7]
	v_rsq_f32_e32 v8, v8
	v_add_co_u32_e32 v72, vcc, s88, v162
	v_pk_add_f32 v[154:155], v[202:203], 1.0 op_sel_hi:[1,0]
	s_nop 0
	v_addc_co_u32_e32 v73, vcc, 0, v163, vcc
	v_add_co_u32_e32 v74, vcc, s89, v162
	v_pk_mul_f32 v[40:41], v[40:41], v[12:13] op_sel_hi:[1,0]
	v_pk_mul_f32 v[42:43], v[42:43], v[12:13] op_sel_hi:[1,0]
	v_pk_mul_f32 v[154:155], v[194:195], v[154:155]
	v_pk_mul_f32 v[78:79], v[78:79], v[148:149] op_sel_hi:[1,0]
	v_addc_co_u32_e32 v75, vcc, 0, v163, vcc
	v_pk_fma_f32 v[42:43], v[158:159], v[42:43], v[2:3]
	v_pk_fma_f32 v[40:41], v[160:161], v[40:41], v[0:1]
	v_pk_fma_f32 v[90:91], v[78:79], v[154:155], v[6:7]
	global_store_dwordx4 v[74:75], v[40:43], off offset:16
	v_add_co_u32_e32 v78, vcc, s90, v162
	s_nop 0
	v_pk_mul_f32 v[40:41], v[146:147], v[10:11] op_sel_hi:[1,0]
	v_pk_mul_f32 v[42:43], v[144:145], v[10:11] op_sel_hi:[1,0]
	v_pk_fma_f32 v[40:41], v[156:157], v[40:41], v[4:5]
	v_pk_fma_f32 v[42:43], v[154:155], v[42:43], v[6:7]
	v_addc_co_u32_e32 v79, vcc, 0, v163, vcc
	v_mul_f32_e32 v9, 0x45800000, v8
	global_store_dwordx4 v[78:79], v[40:43], off
	v_cndmask_b32_e64 v8, v8, v9, s[0:1]
	s_mov_b32 s0, 0xb0000
	v_pk_mul_f32 v[40:41], v[138:139], v[10:11] op_sel_hi:[1,0]
	v_pk_mul_f32 v[42:43], v[136:137], v[10:11] op_sel_hi:[1,0]
	v_pk_fma_f32 v[40:41], v[160:161], v[40:41], v[0:1]
	v_pk_fma_f32 v[42:43], v[158:159], v[42:43], v[2:3]
	v_pk_mul_f32 v[124:125], v[124:125], v[152:153] op_sel_hi:[1,0]
	v_pk_mul_f32 v[126:127], v[126:127], v[152:153] op_sel_hi:[1,0]
	v_pk_mul_f32 v[110:111], v[110:111], v[150:151] op_sel_hi:[1,0]
	v_pk_mul_f32 v[94:95], v[94:95], v[134:135] op_sel_hi:[1,0]
	global_store_dwordx4 v[76:77], v[88:91], off
	v_pk_mul_f32 v[60:61], v[60:61], v[14:15] op_sel_hi:[1,0]
	v_pk_mul_f32 v[62:63], v[62:63], v[14:15] op_sel_hi:[1,0]
	v_pk_mul_f32 v[44:45], v[44:45], v[12:13] op_sel_hi:[1,0]
	v_pk_mul_f32 v[46:47], v[46:47], v[12:13] op_sel_hi:[1,0]
	global_store_dwordx4 v[78:79], v[40:43], off offset:16
	v_add_co_u32_e32 v88, vcc, s0, v162
	s_nop 0
	v_pk_mul_f32 v[40:41], v[142:143], v[8:9] op_sel_hi:[1,0]
	v_pk_mul_f32 v[42:43], v[130:131], v[8:9] op_sel_hi:[1,0]
	v_pk_fma_f32 v[126:127], v[126:127], v[154:155], v[6:7]
	v_pk_fma_f32 v[124:125], v[124:125], v[156:157], v[4:5]
	v_pk_fma_f32 v[122:123], v[110:111], v[154:155], v[6:7]
	v_pk_fma_f32 v[106:107], v[94:95], v[154:155], v[6:7]
	v_pk_fma_f32 v[62:63], v[154:155], v[62:63], v[6:7]
	v_pk_fma_f32 v[60:61], v[156:157], v[60:61], v[4:5]
	v_pk_mul_f32 v[56:57], v[56:57], v[14:15] op_sel_hi:[1,0]
	v_pk_mul_f32 v[58:59], v[58:59], v[14:15] op_sel_hi:[1,0]
	v_pk_fma_f32 v[46:47], v[154:155], v[46:47], v[6:7]
	v_pk_fma_f32 v[44:45], v[156:157], v[44:45], v[4:5]
	v_pk_fma_f32 v[6:7], v[154:155], v[42:43], v[6:7]
	v_pk_fma_f32 v[4:5], v[156:157], v[40:41], v[4:5]
	v_addc_co_u32_e32 v89, vcc, 0, v163, vcc
	v_pk_fma_f32 v[58:59], v[58:59], v[158:159], v[2:3]
	v_pk_fma_f32 v[56:57], v[56:57], v[160:161], v[0:1]
	global_store_dwordx4 v[88:89], v[4:7], off
	global_store_dwordx4 v[72:73], v[56:59], off offset:16
	global_store_dwordx4 v240, v[124:127], s[54:55]
	v_pk_mul_f32 v[4:5], v[140:141], v[8:9] op_sel_hi:[1,0]
	v_pk_mul_f32 v[6:7], v[128:129], v[8:9] op_sel_hi:[1,0]
	v_pk_fma_f32 v[0:1], v[160:161], v[4:5], v[0:1]
	v_pk_fma_f32 v[2:3], v[158:159], v[6:7], v[2:3]
	v_lshlrev_b64 v[56:57], 2, v[132:133]
	global_store_dwordx4 v[108:109], v[120:123], off
	global_store_dwordx4 v[92:93], v[104:107], off
	global_store_dwordx4 v[72:73], v[60:63], off
	global_store_dwordx4 v[74:75], v[44:47], off
	global_store_dwordx4 v[88:89], v[0:3], off offset:16
	s_nop 1
	v_mov_b64_e32 v[4:5], v[208:209]
	v_mov_b64_e32 v[6:7], v[210:211]
	v_mov_b64_e32 v[40:41], v[212:213]
	v_mov_b64_e32 v[42:43], v[214:215]
	v_mov_b64_e32 v[44:45], v[226:227]
	v_mov_b64_e32 v[46:47], v[228:229]
	v_mov_b64_e32 v[56:57], v[230:231]
	v_mov_b64_e32 v[58:59], v[232:233]
	v_mov_b64_e32 v[60:61], v[234:235]
	v_mov_b64_e32 v[62:63], v[236:237]
	v_mov_b64_e32 v[0:1], v[204:205]
	v_mov_b64_e32 v[2:3], v[206:207]
	s_and_b64 vcc, exec, s[4:5]
	s_mov_b64 s[0:1], -1
	v_pk_add_f32 v[2:3], v[2:3], 1.0 op_sel_hi:[1,0]
	v_pk_add_f32 v[0:1], v[0:1], 1.0 op_sel_hi:[1,0]
	v_pk_mul_f32 v[6:7], v[6:7], v[2:3]
	v_pk_mul_f32 v[4:5], v[4:5], v[0:1]
	v_pk_add_f32 v[0:1], v[42:43], 1.0 op_sel_hi:[1,0]
	v_pk_add_f32 v[2:3], v[40:41], 1.0 op_sel_hi:[1,0]
	v_pk_mul_f32 v[40:41], v[46:47], v[0:1]
	v_pk_mul_f32 v[42:43], v[44:45], v[2:3]
	v_pk_mul_f32 v[2:3], v[118:119], v[152:153] op_sel_hi:[1,0]
	v_pk_mul_f32 v[0:1], v[116:117], v[152:153] op_sel_hi:[1,0]
	v_pk_fma_f32 v[2:3], v[2:3], v[6:7], v[58:59]
	v_pk_fma_f32 v[0:1], v[0:1], v[4:5], v[56:57]
	global_store_dwordx4 v240, v[0:3], s[54:55] offset:512
	s_nop 1
	v_pk_mul_f32 v[2:3], v[114:115], v[152:153] op_sel_hi:[1,0]
	v_pk_mul_f32 v[0:1], v[112:113], v[152:153] op_sel_hi:[1,0]
	v_pk_fma_f32 v[2:3], v[2:3], v[40:41], v[62:63]
	v_pk_fma_f32 v[0:1], v[0:1], v[42:43], v[60:61]
	global_store_dwordx4 v240, v[0:3], s[54:55] offset:528
	s_nop 1
	v_pk_mul_f32 v[2:3], v[102:103], v[150:151] op_sel_hi:[1,0]
	v_pk_mul_f32 v[0:1], v[100:101], v[150:151] op_sel_hi:[1,0]
	v_pk_fma_f32 v[2:3], v[2:3], v[6:7], v[58:59]
	v_pk_fma_f32 v[0:1], v[0:1], v[4:5], v[56:57]
	global_store_dwordx4 v[108:109], v[0:3], off offset:512
	s_nop 1
	v_pk_mul_f32 v[2:3], v[98:99], v[150:151] op_sel_hi:[1,0]
	v_pk_mul_f32 v[0:1], v[96:97], v[150:151] op_sel_hi:[1,0]
	v_pk_fma_f32 v[2:3], v[2:3], v[40:41], v[62:63]
	v_pk_fma_f32 v[0:1], v[0:1], v[42:43], v[60:61]
	global_store_dwordx4 v[108:109], v[0:3], off offset:528
	s_nop 1
	v_pk_mul_f32 v[2:3], v[86:87], v[134:135] op_sel_hi:[1,0]
	v_pk_mul_f32 v[0:1], v[84:85], v[134:135] op_sel_hi:[1,0]
	v_pk_fma_f32 v[2:3], v[2:3], v[6:7], v[58:59]
	v_pk_fma_f32 v[0:1], v[0:1], v[4:5], v[56:57]
	global_store_dwordx4 v[92:93], v[0:3], off offset:512
	s_nop 1
	v_pk_mul_f32 v[2:3], v[82:83], v[134:135] op_sel_hi:[1,0]
	v_pk_mul_f32 v[0:1], v[80:81], v[134:135] op_sel_hi:[1,0]
	v_pk_fma_f32 v[2:3], v[2:3], v[40:41], v[62:63]
	v_pk_fma_f32 v[0:1], v[0:1], v[42:43], v[60:61]
	global_store_dwordx4 v[92:93], v[0:3], off offset:528
	s_nop 1
	v_pk_mul_f32 v[2:3], v[70:71], v[148:149] op_sel_hi:[1,0]
	v_pk_mul_f32 v[0:1], v[68:69], v[148:149] op_sel_hi:[1,0]
	v_pk_fma_f32 v[2:3], v[2:3], v[6:7], v[58:59]
	v_pk_fma_f32 v[0:1], v[0:1], v[4:5], v[56:57]
	global_store_dwordx4 v[76:77], v[0:3], off offset:512
	s_nop 1
	v_pk_mul_f32 v[2:3], v[66:67], v[148:149] op_sel_hi:[1,0]
	v_pk_mul_f32 v[0:1], v[64:65], v[148:149] op_sel_hi:[1,0]
	v_pk_fma_f32 v[2:3], v[2:3], v[40:41], v[62:63]
	v_pk_fma_f32 v[0:1], v[0:1], v[42:43], v[60:61]
	global_store_dwordx4 v[76:77], v[0:3], off offset:528
	s_nop 1
	v_pk_mul_f32 v[2:3], v[54:55], v[14:15] op_sel_hi:[1,0]
	v_pk_mul_f32 v[0:1], v[52:53], v[14:15] op_sel_hi:[1,0]
	v_pk_fma_f32 v[2:3], v[2:3], v[6:7], v[58:59]
	v_pk_fma_f32 v[0:1], v[0:1], v[4:5], v[56:57]
	global_store_dwordx4 v[72:73], v[0:3], off offset:512
	s_nop 1
	v_pk_mul_f32 v[2:3], v[50:51], v[14:15] op_sel_hi:[1,0]
	v_pk_mul_f32 v[0:1], v[48:49], v[14:15] op_sel_hi:[1,0]
	v_pk_fma_f32 v[2:3], v[2:3], v[40:41], v[62:63]
	v_pk_fma_f32 v[0:1], v[0:1], v[42:43], v[60:61]
	global_store_dwordx4 v[72:73], v[0:3], off offset:528
	s_nop 1
	v_pk_mul_f32 v[2:3], v[38:39], v[12:13] op_sel_hi:[1,0]
	v_pk_mul_f32 v[0:1], v[36:37], v[12:13] op_sel_hi:[1,0]
	v_pk_fma_f32 v[2:3], v[2:3], v[6:7], v[58:59]
	v_pk_fma_f32 v[0:1], v[0:1], v[4:5], v[56:57]
	global_store_dwordx4 v[74:75], v[0:3], off offset:512
	s_nop 1
	v_pk_mul_f32 v[2:3], v[34:35], v[12:13] op_sel_hi:[1,0]
	v_pk_mul_f32 v[0:1], v[32:33], v[12:13] op_sel_hi:[1,0]
	v_pk_fma_f32 v[2:3], v[2:3], v[40:41], v[62:63]
	v_pk_fma_f32 v[0:1], v[0:1], v[42:43], v[60:61]
	global_store_dwordx4 v[74:75], v[0:3], off offset:528
	s_nop 1
	v_pk_mul_f32 v[2:3], v[22:23], v[10:11] op_sel_hi:[1,0]
	v_pk_mul_f32 v[0:1], v[20:21], v[10:11] op_sel_hi:[1,0]
	v_pk_fma_f32 v[2:3], v[2:3], v[6:7], v[58:59]
	v_pk_fma_f32 v[0:1], v[0:1], v[4:5], v[56:57]
	global_store_dwordx4 v[78:79], v[0:3], off offset:512
	s_nop 1
	v_pk_mul_f32 v[2:3], v[18:19], v[10:11] op_sel_hi:[1,0]
	v_pk_mul_f32 v[0:1], v[16:17], v[10:11] op_sel_hi:[1,0]
	v_pk_fma_f32 v[2:3], v[2:3], v[40:41], v[62:63]
	v_pk_fma_f32 v[0:1], v[0:1], v[42:43], v[60:61]
	global_store_dwordx4 v[78:79], v[0:3], off offset:528
	s_nop 1
	v_pk_mul_f32 v[2:3], v[26:27], v[8:9] op_sel_hi:[1,0]
	v_pk_mul_f32 v[0:1], v[30:31], v[8:9] op_sel_hi:[1,0]
	v_pk_fma_f32 v[2:3], v[2:3], v[6:7], v[58:59]
	v_pk_fma_f32 v[0:1], v[0:1], v[4:5], v[56:57]
	global_store_dwordx4 v[88:89], v[0:3], off offset:512
	s_nop 1
	v_pk_mul_f32 v[2:3], v[24:25], v[8:9] op_sel_hi:[1,0]
	v_pk_mul_f32 v[0:1], v[28:29], v[8:9] op_sel_hi:[1,0]
	v_pk_fma_f32 v[2:3], v[2:3], v[40:41], v[62:63]
	v_pk_fma_f32 v[0:1], v[0:1], v[42:43], v[60:61]
	global_store_dwordx4 v[88:89], v[0:3], off offset:528
	s_cbranch_vccnz .LBB0_709
	v_readlane_b32 s0, v254, 41
	v_readlane_b32 s1, v254, 42
	s_andn2_b64 vcc, exec, s[0:1]
	s_cbranch_vccnz .LBB0_708
	s_barrier
	s_branch .LBB0_708
